# placement pin (doc 9.3): the two attention tile-loop heads and the five GEMM k-loop heads aligned to 64 bytes
# baseline (speedup 1.0000x reference)
; #define PG8_WAIT_V(n) asm volatile("s_waitcnt vmcnt(" #n ")" ::: "memory")
; #define PG8_WAIT_L(n) asm volatile("s_waitcnt lgkmcnt(" #n ")" ::: "memory")
; template <class Epi, class Sched, bool ALIGN_EPI = true>
; __device__ __forceinline__ void gemm_phase(LAS unsigned char* lds, const int wave_s, const int K, const Sched& S, const Epi& E) {
;     ...
;         const bool has_next = S.next(ui + 1, nxt);
;         const char* nA = has_next ? S.aptr(nxt) : cA; const char* nB = has_next ? S.bptr(nxt) : cB;
;         for (int t = 0; t < nt; t += 2) {
;             const bool last = (t == nt - 2);
;             const char* a1 = cA + (size_t)(t + 1) * kstep;
;             const char* a2 = last ? nA : cA + (size_t)(t + 2) * kstep; const char* b2 = last ? nB : cB + (size_t)(t + 2) * kstep;
;             const char* a3 = a2 + kstep; const char* b3 = b2 + kstep;
;             PG8_LDB(B0, 0, 0); PG8_LDB(B1, 0, 1); PG8_SCHED; PG8_LDA(At, 0, 0); PG8_STAGE(PG8_SA(1, 1), a1 + hstep, voffA);
;             PG8_WAIT_V(8); PG8_WAIT_L(0); PG8_BAR; PG8_MMA(0, 0, At, B0); PG8_MMA(0, 1, At, B1); PG8_BAR; PG8_SCHED;
;             PG8_LDA(At, 0, 1); PG8_STAGE(PG8_SB(0, 0), b2, voffB); PG8_STAGE(PG8_SB(0, 1), b2 + hstep, voffB); PG8_STAGE(PG8_SA(0, 0), a2, voffA);
;             PG8_WAIT_V(8); PG8_WAIT_L(0); PG8_BAR; PG8_MMA(1, 0, At, B0); PG8_MMA(1, 1, At, B1); PG8_BAR; PG8_SCHED;
;             PG8_LDB(B0, 1, 0); PG8_LDB(B1, 1, 1); PG8_SCHED; PG8_LDA(At, 1, 0); PG8_STAGE(PG8_SA(0, 1), a2 + hstep, voffA);
;             PG8_WAIT_V(8); PG8_WAIT_L(0); PG8_BAR; PG8_MMA(0, 0, At, B0); PG8_MMA(0, 1, At, B1); PG8_BAR; PG8_SCHED;
;             PG8_LDA(At, 1, 1); PG8_STAGE(PG8_SB(1, 0), b3, voffB); PG8_STAGE(PG8_SB(1, 1), b3 + hstep, voffB); PG8_STAGE(PG8_SA(1, 0), a3, voffA);
;             PG8_WAIT_V(8); PG8_WAIT_L(0); PG8_BAR; PG8_MMA(1, 0, At, B0); PG8_MMA(1, 1, At, B1); PG8_BAR; PG8_SCHED;
;         }
;         if constexpr (ALIGN_EPI) { if (wr == 0) PG8_BAR; }
;         E(acc, cur, wr, wc, fr, fq);
;         if (!has_next) break;
; #pragma unroll
;         for (int a = 0; a < 2; ++a)
; #pragma unroll
;             for (int b = 0; b < 2; ++b)
; #pragma unroll
;                 for (int m = 0; m < 4; ++m)
; #pragma unroll
;                     for (int n = 0; n < 2; ++n) acc[a][b][m][n] = (f32x4){0.f, 0.f, 0.f, 0.f};
;         cur = nxt; cA = nA; cB = nB; ++ui;
.LBB0_64:
	s_ashr_i32 s71, s70, 31
	s_lshl_b64 s[54:55], s[70:71], 21
	s_add_u32 s76, s7, s54
	s_addc_u32 s77, s16, s55
	s_and_b64 s[54:55], s[48:49], exec
	s_cselect_b32 s68, s77, s13
	s_cselect_b32 s69, s76, s12
	s_ashr_i32 s65, s64, 31
	s_lshl_b64 s[54:55], s[64:65], 21
	s_add_u32 s90, s18, s54
	s_addc_u32 s91, s19, s55
	s_and_b64 s[54:55], s[48:49], exec
	s_cselect_b32 s65, s91, s51
	s_cselect_b32 s71, s90, s50
	s_add_u32 s12, s12, 0x100080
	s_addc_u32 s13, s13, 0
	s_add_u32 s79, s50, 0x100
	v_mov_b32_e32 v2, 0
	s_addc_u32 s80, s51, 0
	s_mov_b32 s81, -2
	v_mov_b32_e32 v3, v2
	v_mov_b32_e32 v4, v2
	v_mov_b32_e32 v5, v2
	v_mov_b32_e32 v6, v2
	v_mov_b32_e32 v7, v2
	v_mov_b32_e32 v8, v2
	v_mov_b32_e32 v9, v2
	v_mov_b32_e32 v18, v2
	v_mov_b32_e32 v19, v2
	v_mov_b32_e32 v20, v2
	v_mov_b32_e32 v21, v2
	v_mov_b32_e32 v22, v2
	v_mov_b32_e32 v23, v2
	v_mov_b32_e32 v24, v2
	v_mov_b32_e32 v25, v2
	v_mov_b32_e32 v34, v2
	v_mov_b32_e32 v35, v2
	v_mov_b32_e32 v36, v2
	v_mov_b32_e32 v37, v2
	v_mov_b32_e32 v38, v2
	v_mov_b32_e32 v39, v2
	v_mov_b32_e32 v40, v2
	v_mov_b32_e32 v41, v2
	v_mov_b32_e32 v66, v2
	v_mov_b32_e32 v67, v2
	v_mov_b32_e32 v68, v2
	v_mov_b32_e32 v69, v2
	v_mov_b32_e32 v70, v2
	v_mov_b32_e32 v71, v2
	v_mov_b32_e32 v72, v2
	v_mov_b32_e32 v73, v2
	v_mov_b32_e32 v10, v2
	v_mov_b32_e32 v11, v2
	v_mov_b32_e32 v12, v2
	v_mov_b32_e32 v13, v2
	v_mov_b32_e32 v14, v2
	v_mov_b32_e32 v15, v2
	v_mov_b32_e32 v16, v2
	v_mov_b32_e32 v17, v2
	v_mov_b32_e32 v26, v2
	v_mov_b32_e32 v27, v2
	v_mov_b32_e32 v28, v2
	v_mov_b32_e32 v29, v2
	v_mov_b32_e32 v30, v2
	v_mov_b32_e32 v31, v2
	v_mov_b32_e32 v32, v2
	v_mov_b32_e32 v33, v2
	v_mov_b32_e32 v42, v2
	v_mov_b32_e32 v43, v2
	v_mov_b32_e32 v44, v2
	v_mov_b32_e32 v45, v2
	v_mov_b32_e32 v46, v2
	v_mov_b32_e32 v47, v2
	v_mov_b32_e32 v48, v2
	v_mov_b32_e32 v49, v2
	v_mov_b32_e32 v82, v2
	v_mov_b32_e32 v83, v2
	v_mov_b32_e32 v84, v2
	v_mov_b32_e32 v85, v2
	v_mov_b32_e32 v86, v2
	v_mov_b32_e32 v87, v2
	v_mov_b32_e32 v88, v2
	v_mov_b32_e32 v89, v2
	v_mov_b32_e32 v106, v2
	v_mov_b32_e32 v107, v2
	v_mov_b32_e32 v108, v2
	v_mov_b32_e32 v109, v2
	v_mov_b32_e32 v110, v2
	v_mov_b32_e32 v111, v2
	v_mov_b32_e32 v112, v2
	v_mov_b32_e32 v113, v2
	v_mov_b32_e32 v114, v2
	v_mov_b32_e32 v115, v2
	v_mov_b32_e32 v116, v2
	v_mov_b32_e32 v117, v2
	v_mov_b32_e32 v118, v2
	v_mov_b32_e32 v119, v2
	v_mov_b32_e32 v120, v2
	v_mov_b32_e32 v121, v2
	v_mov_b32_e32 v90, v2
	v_mov_b32_e32 v91, v2
	v_mov_b32_e32 v92, v2
	v_mov_b32_e32 v93, v2
	v_mov_b32_e32 v94, v2
	v_mov_b32_e32 v95, v2
	v_mov_b32_e32 v96, v2
	v_mov_b32_e32 v97, v2
	v_mov_b32_e32 v58, v2
	v_mov_b32_e32 v59, v2
	v_mov_b32_e32 v60, v2
	v_mov_b32_e32 v61, v2
	v_mov_b32_e32 v62, v2
	v_mov_b32_e32 v63, v2
	v_mov_b32_e32 v64, v2
	v_mov_b32_e32 v65, v2
	v_mov_b32_e32 v122, v2
	v_mov_b32_e32 v123, v2
	v_mov_b32_e32 v124, v2
	v_mov_b32_e32 v125, v2
	v_mov_b32_e32 v126, v2
	v_mov_b32_e32 v127, v2
	v_mov_b32_e32 v128, v2
	v_mov_b32_e32 v129, v2
	v_mov_b32_e32 v102, v2
	v_mov_b32_e32 v103, v2
	v_mov_b32_e32 v104, v2
	v_mov_b32_e32 v105, v2
	v_mov_b32_e32 v98, v2
	v_mov_b32_e32 v99, v2
	v_mov_b32_e32 v100, v2
	v_mov_b32_e32 v101, v2
	v_mov_b32_e32 v78, v2
	v_mov_b32_e32 v79, v2
	v_mov_b32_e32 v80, v2
	v_mov_b32_e32 v81, v2
	v_mov_b32_e32 v74, v2
	v_mov_b32_e32 v75, v2
	v_mov_b32_e32 v76, v2
	v_mov_b32_e32 v77, v2
	v_mov_b32_e32 v54, v2
	v_mov_b32_e32 v55, v2
	v_mov_b32_e32 v56, v2
	v_mov_b32_e32 v57, v2
	v_mov_b32_e32 v50, v2
	v_mov_b32_e32 v51, v2
	v_mov_b32_e32 v52, v2
	v_mov_b32_e32 v53, v2
	.p2align	6

; #define PG8_WAIT_V(n) asm volatile("s_waitcnt vmcnt(" #n ")" ::: "memory")
; #define PG8_WAIT_L(n) asm volatile("s_waitcnt lgkmcnt(" #n ")" ::: "memory")
; template <class Epi, class Sched, bool ALIGN_EPI = true>
; __device__ __forceinline__ void gemm_phase(LAS unsigned char* lds, const int wave_s, const int K, const Sched& S, const Epi& E) {
;     ...
;         const bool has_next = S.next(ui + 1, nxt);
;         const char* nA = has_next ? S.aptr(nxt) : cA; const char* nB = has_next ? S.bptr(nxt) : cB;
;         for (int t = 0; t < nt; t += 2) {
;             const bool last = (t == nt - 2);
;             const char* a1 = cA + (size_t)(t + 1) * kstep;
;             const char* a2 = last ? nA : cA + (size_t)(t + 2) * kstep; const char* b2 = last ? nB : cB + (size_t)(t + 2) * kstep;
;             const char* a3 = a2 + kstep; const char* b3 = b2 + kstep;
;             PG8_LDB(B0, 0, 0); PG8_LDB(B1, 0, 1); PG8_SCHED; PG8_LDA(At, 0, 0); PG8_STAGE(PG8_SA(1, 1), a1 + hstep, voffA);
;             PG8_WAIT_V(8); PG8_WAIT_L(0); PG8_BAR; PG8_MMA(0, 0, At, B0); PG8_MMA(0, 1, At, B1); PG8_BAR; PG8_SCHED;
;             PG8_LDA(At, 0, 1); PG8_STAGE(PG8_SB(0, 0), b2, voffB); PG8_STAGE(PG8_SB(0, 1), b2 + hstep, voffB); PG8_STAGE(PG8_SA(0, 0), a2, voffA);
;             PG8_WAIT_V(8); PG8_WAIT_L(0); PG8_BAR; PG8_MMA(1, 0, At, B0); PG8_MMA(1, 1, At, B1); PG8_BAR; PG8_SCHED;
;             PG8_LDB(B0, 1, 0); PG8_LDB(B1, 1, 1); PG8_SCHED; PG8_LDA(At, 1, 0); PG8_STAGE(PG8_SA(0, 1), a2 + hstep, voffA);
;             PG8_WAIT_V(8); PG8_WAIT_L(0); PG8_BAR; PG8_MMA(0, 0, At, B0); PG8_MMA(0, 1, At, B1); PG8_BAR; PG8_SCHED;
;             PG8_LDA(At, 1, 1); PG8_STAGE(PG8_SB(1, 0), b3, voffB); PG8_STAGE(PG8_SB(1, 1), b3 + hstep, voffB); PG8_STAGE(PG8_SA(1, 0), a3, voffA);
;             PG8_WAIT_V(8); PG8_WAIT_L(0); PG8_BAR; PG8_MMA(1, 0, At, B0); PG8_MMA(1, 1, At, B1); PG8_BAR; PG8_SCHED;
;         }
;         if constexpr (ALIGN_EPI) { if (wr == 0) PG8_BAR; }
;         E(acc, cur, wr, wc, fr, fq);
;         if (!has_next) break;
; #pragma unroll
;         for (int a = 0; a < 2; ++a)
; #pragma unroll
;             for (int b = 0; b < 2; ++b)
; #pragma unroll
;                 for (int m = 0; m < 4; ++m)
; #pragma unroll
;                     for (int n = 0; n < 2; ++n) acc[a][b][m][n] = (f32x4){0.f, 0.f, 0.f, 0.f};
;         cur = nxt; cA = nA; cB = nB; ++ui;
.LBB0_159:
	s_ashr_i32 s35, s34, 31
	s_lshl_b64 s[44:45], s[34:35], 19
	s_add_u32 s44, s4, s44
	s_addc_u32 s45, s5, s45
	s_and_b64 s[46:47], s[42:43], exec
	s_cselect_b32 s35, s45, s49
	s_cselect_b32 s56, s44, s48
	s_ashr_i32 s15, s14, 31
	s_lshl_b64 s[46:47], s[14:15], 19
	s_add_u32 s46, s7, s46
	s_addc_u32 s47, s16, s47
	s_and_b64 s[52:53], s[42:43], exec
	s_cselect_b32 s15, s47, s51
	s_cselect_b32 s57, s46, s50
	s_add_u32 s48, s48, 0x40080
	s_addc_u32 s49, s49, 0
	s_add_u32 s60, s50, 0x100
	v_mov_b32_e32 v2, 0
	s_addc_u32 s61, s51, 0
	s_mov_b32 s62, -2
	v_mov_b32_e32 v3, v2
	v_mov_b32_e32 v4, v2
	v_mov_b32_e32 v5, v2
	v_mov_b32_e32 v6, v2
	v_mov_b32_e32 v7, v2
	v_mov_b32_e32 v8, v2
	v_mov_b32_e32 v9, v2
	v_mov_b32_e32 v18, v2
	v_mov_b32_e32 v19, v2
	v_mov_b32_e32 v20, v2
	v_mov_b32_e32 v21, v2
	v_mov_b32_e32 v22, v2
	v_mov_b32_e32 v23, v2
	v_mov_b32_e32 v24, v2
	v_mov_b32_e32 v25, v2
	v_mov_b32_e32 v34, v2
	v_mov_b32_e32 v35, v2
	v_mov_b32_e32 v36, v2
	v_mov_b32_e32 v37, v2
	v_mov_b32_e32 v38, v2
	v_mov_b32_e32 v39, v2
	v_mov_b32_e32 v40, v2
	v_mov_b32_e32 v41, v2
	v_mov_b32_e32 v50, v2
	v_mov_b32_e32 v51, v2
	v_mov_b32_e32 v52, v2
	v_mov_b32_e32 v53, v2
	v_mov_b32_e32 v54, v2
	v_mov_b32_e32 v55, v2
	v_mov_b32_e32 v56, v2
	v_mov_b32_e32 v57, v2
	v_mov_b32_e32 v10, v2
	v_mov_b32_e32 v11, v2
	v_mov_b32_e32 v12, v2
	v_mov_b32_e32 v13, v2
	v_mov_b32_e32 v14, v2
	v_mov_b32_e32 v15, v2
	v_mov_b32_e32 v16, v2
	v_mov_b32_e32 v17, v2
	v_mov_b32_e32 v26, v2
	v_mov_b32_e32 v27, v2
	v_mov_b32_e32 v28, v2
	v_mov_b32_e32 v29, v2
	v_mov_b32_e32 v30, v2
	v_mov_b32_e32 v31, v2
	v_mov_b32_e32 v32, v2
	v_mov_b32_e32 v33, v2
	v_mov_b32_e32 v42, v2
	v_mov_b32_e32 v43, v2
	v_mov_b32_e32 v44, v2
	v_mov_b32_e32 v45, v2
	v_mov_b32_e32 v46, v2
	v_mov_b32_e32 v47, v2
	v_mov_b32_e32 v48, v2
	v_mov_b32_e32 v49, v2
	v_mov_b32_e32 v58, v2
	v_mov_b32_e32 v59, v2
	v_mov_b32_e32 v60, v2
	v_mov_b32_e32 v61, v2
	v_mov_b32_e32 v62, v2
	v_mov_b32_e32 v63, v2
	v_mov_b32_e32 v64, v2
	v_mov_b32_e32 v65, v2
	v_mov_b32_e32 v66, v2
	v_mov_b32_e32 v67, v2
	v_mov_b32_e32 v68, v2
	v_mov_b32_e32 v69, v2
	v_mov_b32_e32 v70, v2
	v_mov_b32_e32 v71, v2
	v_mov_b32_e32 v72, v2
	v_mov_b32_e32 v73, v2
	v_mov_b32_e32 v82, v2
	v_mov_b32_e32 v83, v2
	v_mov_b32_e32 v84, v2
	v_mov_b32_e32 v85, v2
	v_mov_b32_e32 v86, v2
	v_mov_b32_e32 v87, v2
	v_mov_b32_e32 v88, v2
	v_mov_b32_e32 v89, v2
	v_mov_b32_e32 v98, v2
	v_mov_b32_e32 v99, v2
	v_mov_b32_e32 v100, v2
	v_mov_b32_e32 v101, v2
	v_mov_b32_e32 v102, v2
	v_mov_b32_e32 v103, v2
	v_mov_b32_e32 v104, v2
	v_mov_b32_e32 v105, v2
	v_mov_b32_e32 v114, v2
	v_mov_b32_e32 v115, v2
	v_mov_b32_e32 v116, v2
	v_mov_b32_e32 v117, v2
	v_mov_b32_e32 v118, v2
	v_mov_b32_e32 v119, v2
	v_mov_b32_e32 v120, v2
	v_mov_b32_e32 v121, v2
	v_mov_b32_e32 v74, v2
	v_mov_b32_e32 v75, v2
	v_mov_b32_e32 v76, v2
	v_mov_b32_e32 v77, v2
	v_mov_b32_e32 v78, v2
	v_mov_b32_e32 v79, v2
	v_mov_b32_e32 v80, v2
	v_mov_b32_e32 v81, v2
	v_mov_b32_e32 v90, v2
	v_mov_b32_e32 v91, v2
	v_mov_b32_e32 v92, v2
	v_mov_b32_e32 v93, v2
	v_mov_b32_e32 v94, v2
	v_mov_b32_e32 v95, v2
	v_mov_b32_e32 v96, v2
	v_mov_b32_e32 v97, v2
	v_mov_b32_e32 v106, v2
	v_mov_b32_e32 v107, v2
	v_mov_b32_e32 v108, v2
	v_mov_b32_e32 v109, v2
	v_mov_b32_e32 v110, v2
	v_mov_b32_e32 v111, v2
	v_mov_b32_e32 v112, v2
	v_mov_b32_e32 v113, v2
	v_mov_b32_e32 v122, v2
	v_mov_b32_e32 v123, v2
	v_mov_b32_e32 v124, v2
	v_mov_b32_e32 v125, v2
	v_mov_b32_e32 v126, v2
	v_mov_b32_e32 v127, v2
	v_mov_b32_e32 v128, v2
	v_mov_b32_e32 v129, v2
	.p2align	6

; #define PG8_WAIT_V(n) asm volatile("s_waitcnt vmcnt(" #n ")" ::: "memory")
; #define PG8_WAIT_L(n) asm volatile("s_waitcnt lgkmcnt(" #n ")" ::: "memory")
; template <class Epi, class Sched, bool ALIGN_EPI = true>
; __device__ __forceinline__ void gemm_phase(LAS unsigned char* lds, const int wave_s, const int K, const Sched& S, const Epi& E) {
;     ...
;         const bool has_next = S.next(ui + 1, nxt);
;         const char* nA = has_next ? S.aptr(nxt) : cA; const char* nB = has_next ? S.bptr(nxt) : cB;
;         for (int t = 0; t < nt; t += 2) {
;             const bool last = (t == nt - 2);
;             const char* a1 = cA + (size_t)(t + 1) * kstep;
;             const char* a2 = last ? nA : cA + (size_t)(t + 2) * kstep; const char* b2 = last ? nB : cB + (size_t)(t + 2) * kstep;
;             const char* a3 = a2 + kstep; const char* b3 = b2 + kstep;
;             PG8_LDB(B0, 0, 0); PG8_LDB(B1, 0, 1); PG8_SCHED; PG8_LDA(At, 0, 0); PG8_STAGE(PG8_SA(1, 1), a1 + hstep, voffA);
;             PG8_WAIT_V(8); PG8_WAIT_L(0); PG8_BAR; PG8_MMA(0, 0, At, B0); PG8_MMA(0, 1, At, B1); PG8_BAR; PG8_SCHED;
;             PG8_LDA(At, 0, 1); PG8_STAGE(PG8_SB(0, 0), b2, voffB); PG8_STAGE(PG8_SB(0, 1), b2 + hstep, voffB); PG8_STAGE(PG8_SA(0, 0), a2, voffA);
;             PG8_WAIT_V(8); PG8_WAIT_L(0); PG8_BAR; PG8_MMA(1, 0, At, B0); PG8_MMA(1, 1, At, B1); PG8_BAR; PG8_SCHED;
;             PG8_LDB(B0, 1, 0); PG8_LDB(B1, 1, 1); PG8_SCHED; PG8_LDA(At, 1, 0); PG8_STAGE(PG8_SA(0, 1), a2 + hstep, voffA);
;             PG8_WAIT_V(8); PG8_WAIT_L(0); PG8_BAR; PG8_MMA(0, 0, At, B0); PG8_MMA(0, 1, At, B1); PG8_BAR; PG8_SCHED;
;             PG8_LDA(At, 1, 1); PG8_STAGE(PG8_SB(1, 0), b3, voffB); PG8_STAGE(PG8_SB(1, 1), b3 + hstep, voffB); PG8_STAGE(PG8_SA(1, 0), a3, voffA);
;             PG8_WAIT_V(8); PG8_WAIT_L(0); PG8_BAR; PG8_MMA(1, 0, At, B0); PG8_MMA(1, 1, At, B1); PG8_BAR; PG8_SCHED;
;         }
;         if constexpr (ALIGN_EPI) { if (wr == 0) PG8_BAR; }
;         E(acc, cur, wr, wc, fr, fq);
;         if (!has_next) break;
; #pragma unroll
;         for (int a = 0; a < 2; ++a)
; #pragma unroll
;             for (int b = 0; b < 2; ++b)
; #pragma unroll
;                 for (int m = 0; m < 4; ++m)
; #pragma unroll
;                     for (int n = 0; n < 2; ++n) acc[a][b][m][n] = (f32x4){0.f, 0.f, 0.f, 0.f};
;         cur = nxt; cA = nA; cB = nB; ++ui;
.LBB0_196:
	s_ashr_i32 s91, s90, 31
	s_lshl_b64 s[54:55], s[90:91], 19
	s_add_u32 s94, s7, s54
	s_addc_u32 s95, s16, s55
	s_and_b64 s[54:55], s[48:49], exec
	s_cselect_b32 s68, s95, s13
	s_cselect_b32 s69, s94, s12
	s_ashr_i32 s79, s78, 31
	s_lshl_b64 s[54:55], s[78:79], 19
	s_add_u32 s60, s39, s54
	s_addc_u32 s61, s87, s55
	s_and_b64 s[54:55], s[48:49], exec
	s_cselect_b32 s73, s61, s51
	s_cselect_b32 s77, s60, s50
	s_add_u32 s12, s12, 0x40080
	s_addc_u32 s13, s13, 0
	s_add_u32 s79, s50, 0x100
	v_mov_b32_e32 v2, 0
	s_addc_u32 s80, s51, 0
	s_mov_b32 s81, -2
	v_mov_b32_e32 v3, v2
	v_mov_b32_e32 v4, v2
	v_mov_b32_e32 v5, v2
	v_mov_b32_e32 v6, v2
	v_mov_b32_e32 v7, v2
	v_mov_b32_e32 v8, v2
	v_mov_b32_e32 v9, v2
	v_mov_b32_e32 v18, v2
	v_mov_b32_e32 v19, v2
	v_mov_b32_e32 v20, v2
	v_mov_b32_e32 v21, v2
	v_mov_b32_e32 v22, v2
	v_mov_b32_e32 v23, v2
	v_mov_b32_e32 v24, v2
	v_mov_b32_e32 v25, v2
	v_mov_b32_e32 v34, v2
	v_mov_b32_e32 v35, v2
	v_mov_b32_e32 v36, v2
	v_mov_b32_e32 v37, v2
	v_mov_b32_e32 v38, v2
	v_mov_b32_e32 v39, v2
	v_mov_b32_e32 v40, v2
	v_mov_b32_e32 v41, v2
	v_mov_b32_e32 v74, v2
	v_mov_b32_e32 v75, v2
	v_mov_b32_e32 v76, v2
	v_mov_b32_e32 v77, v2
	v_mov_b32_e32 v78, v2
	v_mov_b32_e32 v79, v2
	v_mov_b32_e32 v80, v2
	v_mov_b32_e32 v81, v2
	v_mov_b32_e32 v10, v2
	v_mov_b32_e32 v11, v2
	v_mov_b32_e32 v12, v2
	v_mov_b32_e32 v13, v2
	v_mov_b32_e32 v14, v2
	v_mov_b32_e32 v15, v2
	v_mov_b32_e32 v16, v2
	v_mov_b32_e32 v17, v2
	v_mov_b32_e32 v26, v2
	v_mov_b32_e32 v27, v2
	v_mov_b32_e32 v28, v2
	v_mov_b32_e32 v29, v2
	v_mov_b32_e32 v30, v2
	v_mov_b32_e32 v31, v2
	v_mov_b32_e32 v32, v2
	v_mov_b32_e32 v33, v2
	v_mov_b32_e32 v50, v2
	v_mov_b32_e32 v51, v2
	v_mov_b32_e32 v52, v2
	v_mov_b32_e32 v53, v2
	v_mov_b32_e32 v54, v2
	v_mov_b32_e32 v55, v2
	v_mov_b32_e32 v56, v2
	v_mov_b32_e32 v57, v2
	v_mov_b32_e32 v90, v2
	v_mov_b32_e32 v91, v2
	v_mov_b32_e32 v92, v2
	v_mov_b32_e32 v93, v2
	v_mov_b32_e32 v94, v2
	v_mov_b32_e32 v95, v2
	v_mov_b32_e32 v96, v2
	v_mov_b32_e32 v97, v2
	v_mov_b32_e32 v114, v2
	v_mov_b32_e32 v115, v2
	v_mov_b32_e32 v116, v2
	v_mov_b32_e32 v117, v2
	v_mov_b32_e32 v118, v2
	v_mov_b32_e32 v119, v2
	v_mov_b32_e32 v120, v2
	v_mov_b32_e32 v121, v2
	v_mov_b32_e32 v106, v2
	v_mov_b32_e32 v107, v2
	v_mov_b32_e32 v108, v2
	v_mov_b32_e32 v109, v2
	v_mov_b32_e32 v110, v2
	v_mov_b32_e32 v111, v2
	v_mov_b32_e32 v112, v2
	v_mov_b32_e32 v113, v2
	v_mov_b32_e32 v82, v2
	v_mov_b32_e32 v83, v2
	v_mov_b32_e32 v84, v2
	v_mov_b32_e32 v85, v2
	v_mov_b32_e32 v86, v2
	v_mov_b32_e32 v87, v2
	v_mov_b32_e32 v88, v2
	v_mov_b32_e32 v89, v2
	v_mov_b32_e32 v58, v2
	v_mov_b32_e32 v59, v2
	v_mov_b32_e32 v60, v2
	v_mov_b32_e32 v61, v2
	v_mov_b32_e32 v62, v2
	v_mov_b32_e32 v63, v2
	v_mov_b32_e32 v64, v2
	v_mov_b32_e32 v65, v2
	v_mov_b32_e32 v126, v2
	v_mov_b32_e32 v127, v2
	v_mov_b32_e32 v128, v2
	v_mov_b32_e32 v129, v2
	v_mov_b32_e32 v122, v2
	v_mov_b32_e32 v123, v2
	v_mov_b32_e32 v124, v2
	v_mov_b32_e32 v125, v2
	v_mov_b32_e32 v102, v2
	v_mov_b32_e32 v103, v2
	v_mov_b32_e32 v104, v2
	v_mov_b32_e32 v105, v2
	v_mov_b32_e32 v98, v2
	v_mov_b32_e32 v99, v2
	v_mov_b32_e32 v100, v2
	v_mov_b32_e32 v101, v2
	v_mov_b32_e32 v70, v2
	v_mov_b32_e32 v71, v2
	v_mov_b32_e32 v72, v2
	v_mov_b32_e32 v73, v2
	v_mov_b32_e32 v66, v2
	v_mov_b32_e32 v67, v2
	v_mov_b32_e32 v68, v2
	v_mov_b32_e32 v69, v2
	v_mov_b32_e32 v46, v2
	v_mov_b32_e32 v47, v2
	v_mov_b32_e32 v48, v2
	v_mov_b32_e32 v49, v2
	v_mov_b32_e32 v42, v2
	v_mov_b32_e32 v43, v2
	v_mov_b32_e32 v44, v2
	v_mov_b32_e32 v45, v2
	.p2align	6

; template <class Epi, class Sched, bool ALIGN_EPI = true>
; __device__ __forceinline__ void gemm_phase(LAS unsigned char* lds, const int wave_s, const int K, const Sched& S, const Epi& E) {
;     ...
;         for (int a = 0; a < 2; ++a)
; #pragma unroll
;             for (int b = 0; b < 2; ++b)
; #pragma unroll
;                 for (int m = 0; m < 4; ++m)
; #pragma unroll
;                     for (int n = 0; n < 2; ++n) acc[a][b][m][n] = (f32x4){0.f, 0.f, 0.f, 0.f};
;         cur = nxt; cA = nA; cB = nB; ++ui;
.LBB0_298:
	s_add_u32 s12, s12, 0x40080
	s_addc_u32 s13, s13, 0
	s_add_u32 s18, s44, 0x100
	v_mov_b32_e32 v2, 0
	s_addc_u32 s19, s45, 0
	s_mov_b32 s30, -2
	v_mov_b32_e32 v3, v2
	v_mov_b32_e32 v4, v2
	v_mov_b32_e32 v5, v2
	v_mov_b32_e32 v6, v2
	v_mov_b32_e32 v7, v2
	v_mov_b32_e32 v8, v2
	v_mov_b32_e32 v9, v2
	v_mov_b32_e32 v10, v2
	v_mov_b32_e32 v11, v2
	v_mov_b32_e32 v12, v2
	v_mov_b32_e32 v13, v2
	v_mov_b32_e32 v14, v2
	v_mov_b32_e32 v15, v2
	v_mov_b32_e32 v16, v2
	v_mov_b32_e32 v17, v2
	v_mov_b32_e32 v18, v2
	v_mov_b32_e32 v19, v2
	v_mov_b32_e32 v20, v2
	v_mov_b32_e32 v21, v2
	v_mov_b32_e32 v22, v2
	v_mov_b32_e32 v23, v2
	v_mov_b32_e32 v24, v2
	v_mov_b32_e32 v25, v2
	v_mov_b32_e32 v26, v2
	v_mov_b32_e32 v27, v2
	v_mov_b32_e32 v28, v2
	v_mov_b32_e32 v29, v2
	v_mov_b32_e32 v30, v2
	v_mov_b32_e32 v31, v2
	v_mov_b32_e32 v32, v2
	v_mov_b32_e32 v33, v2
	v_mov_b32_e32 v66, v2
	v_mov_b32_e32 v67, v2
	v_mov_b32_e32 v68, v2
	v_mov_b32_e32 v69, v2
	v_mov_b32_e32 v70, v2
	v_mov_b32_e32 v71, v2
	v_mov_b32_e32 v72, v2
	v_mov_b32_e32 v73, v2
	v_mov_b32_e32 v74, v2
	v_mov_b32_e32 v75, v2
	v_mov_b32_e32 v76, v2
	v_mov_b32_e32 v77, v2
	v_mov_b32_e32 v78, v2
	v_mov_b32_e32 v79, v2
	v_mov_b32_e32 v80, v2
	v_mov_b32_e32 v81, v2
	v_mov_b32_e32 v82, v2
	v_mov_b32_e32 v83, v2
	v_mov_b32_e32 v84, v2
	v_mov_b32_e32 v85, v2
	v_mov_b32_e32 v86, v2
	v_mov_b32_e32 v87, v2
	v_mov_b32_e32 v88, v2
	v_mov_b32_e32 v89, v2
	v_mov_b32_e32 v90, v2
	v_mov_b32_e32 v91, v2
	v_mov_b32_e32 v92, v2
	v_mov_b32_e32 v93, v2
	v_mov_b32_e32 v94, v2
	v_mov_b32_e32 v95, v2
	v_mov_b32_e32 v96, v2
	v_mov_b32_e32 v97, v2
	v_mov_b32_e32 v34, v2
	v_mov_b32_e32 v35, v2
	v_mov_b32_e32 v36, v2
	v_mov_b32_e32 v37, v2
	v_mov_b32_e32 v38, v2
	v_mov_b32_e32 v39, v2
	v_mov_b32_e32 v40, v2
	v_mov_b32_e32 v41, v2
	v_mov_b32_e32 v42, v2
	v_mov_b32_e32 v43, v2
	v_mov_b32_e32 v44, v2
	v_mov_b32_e32 v45, v2
	v_mov_b32_e32 v46, v2
	v_mov_b32_e32 v47, v2
	v_mov_b32_e32 v48, v2
	v_mov_b32_e32 v49, v2
	v_mov_b32_e32 v50, v2
	v_mov_b32_e32 v51, v2
	v_mov_b32_e32 v52, v2
	v_mov_b32_e32 v53, v2
	v_mov_b32_e32 v54, v2
	v_mov_b32_e32 v55, v2
	v_mov_b32_e32 v56, v2
	v_mov_b32_e32 v57, v2
	v_mov_b32_e32 v58, v2
	v_mov_b32_e32 v59, v2
	v_mov_b32_e32 v60, v2
	v_mov_b32_e32 v61, v2
	v_mov_b32_e32 v62, v2
	v_mov_b32_e32 v63, v2
	v_mov_b32_e32 v64, v2
	v_mov_b32_e32 v65, v2
	v_mov_b32_e32 v98, v2
	v_mov_b32_e32 v99, v2
	v_mov_b32_e32 v100, v2
	v_mov_b32_e32 v101, v2
	v_mov_b32_e32 v102, v2
	v_mov_b32_e32 v103, v2
	v_mov_b32_e32 v104, v2
	v_mov_b32_e32 v105, v2
	v_mov_b32_e32 v106, v2
	v_mov_b32_e32 v107, v2
	v_mov_b32_e32 v108, v2
	v_mov_b32_e32 v109, v2
	v_mov_b32_e32 v110, v2
	v_mov_b32_e32 v111, v2
	v_mov_b32_e32 v112, v2
	v_mov_b32_e32 v113, v2
	v_mov_b32_e32 v114, v2
	v_mov_b32_e32 v115, v2
	v_mov_b32_e32 v116, v2
	v_mov_b32_e32 v117, v2
	v_mov_b32_e32 v118, v2
	v_mov_b32_e32 v119, v2
	v_mov_b32_e32 v120, v2
	v_mov_b32_e32 v121, v2
	v_mov_b32_e32 v122, v2
	v_mov_b32_e32 v123, v2
	v_mov_b32_e32 v124, v2
	v_mov_b32_e32 v125, v2
	v_mov_b32_e32 v126, v2
	v_mov_b32_e32 v127, v2
	v_mov_b32_e32 v128, v2
	v_mov_b32_e32 v129, v2
	.p2align	6

; template <class Epi, class Sched, bool ALIGN_EPI = true>
; __device__ __forceinline__ void gemm_phase(LAS unsigned char* lds, const int wave_s, const int K, const Sched& S, const Epi& E) {
;     ...
;         const bool has_next = S.next(ui + 1, nxt);
;         const char* nA = has_next ? S.aptr(nxt) : cA; const char* nB = has_next ? S.bptr(nxt) : cB;
;         for (int t = 0; t < nt; t += 2) {
;             const bool last = (t == nt - 2);
;             const char* a1 = cA + (size_t)(t + 1) * kstep;
;             const char* a2 = last ? nA : cA + (size_t)(t + 2) * kstep; const char* b2 = last ? nB : cB + (size_t)(t + 2) * kstep;
;             const char* a3 = a2 + kstep; const char* b3 = b2 + kstep;
;             PG8_LDB(B0, 0, 0); PG8_LDB(B1, 0, 1); PG8_SCHED; PG8_LDA(At, 0, 0); PG8_STAGE(PG8_SA(1, 1), a1 + hstep, voffA);
;             PG8_WAIT_V(8); PG8_WAIT_L(0); PG8_BAR; PG8_MMA(0, 0, At, B0); PG8_MMA(0, 1, At, B1); PG8_BAR; PG8_SCHED;
;             PG8_LDA(At, 0, 1); PG8_STAGE(PG8_SB(0, 0), b2, voffB); PG8_STAGE(PG8_SB(0, 1), b2 + hstep, voffB); PG8_STAGE(PG8_SA(0, 0), a2, voffA);
;             PG8_WAIT_V(8); PG8_WAIT_L(0); PG8_BAR; PG8_MMA(1, 0, At, B0); PG8_MMA(1, 1, At, B1); PG8_BAR; PG8_SCHED;
;             PG8_LDB(B0, 1, 0); PG8_LDB(B1, 1, 1); PG8_SCHED; PG8_LDA(At, 1, 0); PG8_STAGE(PG8_SA(0, 1), a2 + hstep, voffA);
;             PG8_WAIT_V(8); PG8_WAIT_L(0); PG8_BAR; PG8_MMA(0, 0, At, B0); PG8_MMA(0, 1, At, B1); PG8_BAR; PG8_SCHED;
;             PG8_LDA(At, 1, 1); PG8_STAGE(PG8_SB(1, 0), b3, voffB); PG8_STAGE(PG8_SB(1, 1), b3 + hstep, voffB); PG8_STAGE(PG8_SA(1, 0), a3, voffA);
;             PG8_WAIT_V(8); PG8_WAIT_L(0); PG8_BAR; PG8_MMA(1, 0, At, B0); PG8_MMA(1, 1, At, B1); PG8_BAR; PG8_SCHED;
;         }
;         if constexpr (ALIGN_EPI) { if (wr == 0) PG8_BAR; }
;         E(acc, cur, wr, wc, fr, fq);
;         if (!has_next) break;
; #pragma unroll
;         for (int a = 0; a < 2; ++a)
; #pragma unroll
;             for (int b = 0; b < 2; ++b)
; #pragma unroll
;                 for (int m = 0; m < 4; ++m)
; #pragma unroll
;     __device__ __forceinline__ bool next(int i, Unit& u) const {
;     ...
;         if (L < 64 * 24) { pg8::tile_map(L, 64, 24, u.pm, u.pn); u.j = 0; return true; }
;         const int L1 = L - 64 * 24; if (L1 >= 4 * 64) return false;
;         pg8::tile_map(L1, 4, 64, u.pm, u.pn); u.j = 1; return true;
;     }
.LBB0_424:
	s_lshl_b32 s15, s81, 8
	s_addk_i32 s15, 0x1800
	s_cmp_eq_u32 s80, 0
	s_cselect_b32 s20, s81, s15
	s_cselect_b32 s15, 19, 11
	s_cselect_b32 s19, s5, s9
	s_cselect_b32 s28, s4, s8
	s_cselect_b32 s30, s8, s4
	s_cselect_b32 s36, s9, s5
	s_ashr_i32 s21, s20, 31
	s_lshl_b64 s[20:21], s[20:21], s15
	s_add_u32 s70, s28, s20
	s_addc_u32 s71, s19, s21
	s_and_b64 s[20:21], s[76:77], exec
	s_cselect_b32 s19, s71, s13
	s_cselect_b32 s20, s70, s12
	s_ashr_i32 s15, s14, 31
	s_lshl_b64 s[44:45], s[14:15], 19
	s_add_u32 s90, s30, s44
	s_addc_u32 s91, s36, s45
	s_and_b64 s[44:45], s[76:77], exec
	s_cselect_b32 s15, s91, s35
	s_cselect_b32 s21, s90, s34
	s_add_u32 s12, s12, 0x40080
	s_addc_u32 s13, s13, 0
	s_add_u32 s28, s34, 0x100
	v_mov_b32_e32 v2, 0
	s_addc_u32 s30, s35, 0
	s_mov_b32 s36, -2
	v_mov_b32_e32 v3, v2
	v_mov_b32_e32 v4, v2
	v_mov_b32_e32 v5, v2
	v_mov_b32_e32 v6, v2
	v_mov_b32_e32 v7, v2
	v_mov_b32_e32 v8, v2
	v_mov_b32_e32 v9, v2
	v_mov_b32_e32 v10, v2
	v_mov_b32_e32 v11, v2
	v_mov_b32_e32 v12, v2
	v_mov_b32_e32 v13, v2
	v_mov_b32_e32 v14, v2
	v_mov_b32_e32 v15, v2
	v_mov_b32_e32 v16, v2
	v_mov_b32_e32 v17, v2
	v_mov_b32_e32 v26, v2
	v_mov_b32_e32 v27, v2
	v_mov_b32_e32 v28, v2
	v_mov_b32_e32 v29, v2
	v_mov_b32_e32 v30, v2
	v_mov_b32_e32 v31, v2
	v_mov_b32_e32 v32, v2
	v_mov_b32_e32 v33, v2
	v_mov_b32_e32 v42, v2
	v_mov_b32_e32 v43, v2
	v_mov_b32_e32 v44, v2
	v_mov_b32_e32 v45, v2
	v_mov_b32_e32 v46, v2
	v_mov_b32_e32 v47, v2
	v_mov_b32_e32 v48, v2
	v_mov_b32_e32 v49, v2
	v_mov_b32_e32 v18, v2
	v_mov_b32_e32 v19, v2
	v_mov_b32_e32 v20, v2
	v_mov_b32_e32 v21, v2
	v_mov_b32_e32 v22, v2
	v_mov_b32_e32 v23, v2
	v_mov_b32_e32 v24, v2
	v_mov_b32_e32 v25, v2
	v_mov_b32_e32 v34, v2
	v_mov_b32_e32 v35, v2
	v_mov_b32_e32 v36, v2
	v_mov_b32_e32 v37, v2
	v_mov_b32_e32 v38, v2
	v_mov_b32_e32 v39, v2
	v_mov_b32_e32 v40, v2
	v_mov_b32_e32 v41, v2
	v_mov_b32_e32 v50, v2
	v_mov_b32_e32 v51, v2
	v_mov_b32_e32 v52, v2
	v_mov_b32_e32 v53, v2
	v_mov_b32_e32 v54, v2
	v_mov_b32_e32 v55, v2
	v_mov_b32_e32 v56, v2
	v_mov_b32_e32 v57, v2
	v_mov_b32_e32 v58, v2
	v_mov_b32_e32 v59, v2
	v_mov_b32_e32 v60, v2
	v_mov_b32_e32 v61, v2
	v_mov_b32_e32 v62, v2
	v_mov_b32_e32 v63, v2
	v_mov_b32_e32 v64, v2
	v_mov_b32_e32 v65, v2
	v_mov_b32_e32 v66, v2
	v_mov_b32_e32 v67, v2
	v_mov_b32_e32 v68, v2
	v_mov_b32_e32 v69, v2
	v_mov_b32_e32 v70, v2
	v_mov_b32_e32 v71, v2
	v_mov_b32_e32 v72, v2
	v_mov_b32_e32 v73, v2
	v_mov_b32_e32 v74, v2
	v_mov_b32_e32 v75, v2
	v_mov_b32_e32 v76, v2
	v_mov_b32_e32 v77, v2
	v_mov_b32_e32 v82, v2
	v_mov_b32_e32 v83, v2
	v_mov_b32_e32 v84, v2
	v_mov_b32_e32 v85, v2
	v_mov_b32_e32 v90, v2
	v_mov_b32_e32 v91, v2
	v_mov_b32_e32 v92, v2
	v_mov_b32_e32 v93, v2
	v_mov_b32_e32 v98, v2
	v_mov_b32_e32 v99, v2
	v_mov_b32_e32 v100, v2
	v_mov_b32_e32 v101, v2
	v_mov_b32_e32 v106, v2
	v_mov_b32_e32 v107, v2
	v_mov_b32_e32 v108, v2
	v_mov_b32_e32 v109, v2
	v_mov_b32_e32 v114, v2
	v_mov_b32_e32 v115, v2
	v_mov_b32_e32 v116, v2
	v_mov_b32_e32 v117, v2
	v_mov_b32_e32 v78, v2
	v_mov_b32_e32 v79, v2
	v_mov_b32_e32 v80, v2
	v_mov_b32_e32 v81, v2
	v_mov_b32_e32 v86, v2
	v_mov_b32_e32 v87, v2
	v_mov_b32_e32 v88, v2
	v_mov_b32_e32 v89, v2
	v_mov_b32_e32 v94, v2
	v_mov_b32_e32 v95, v2
	v_mov_b32_e32 v96, v2
	v_mov_b32_e32 v97, v2
	v_mov_b32_e32 v102, v2
	v_mov_b32_e32 v103, v2
	v_mov_b32_e32 v104, v2
	v_mov_b32_e32 v105, v2
	v_mov_b32_e32 v110, v2
	v_mov_b32_e32 v111, v2
	v_mov_b32_e32 v112, v2
	v_mov_b32_e32 v113, v2
	v_mov_b32_e32 v118, v2
	v_mov_b32_e32 v119, v2
	v_mov_b32_e32 v120, v2
	v_mov_b32_e32 v121, v2
	v_mov_b32_e32 v122, v2
	v_mov_b32_e32 v123, v2
	v_mov_b32_e32 v124, v2
	v_mov_b32_e32 v125, v2
	v_mov_b32_e32 v126, v2
	v_mov_b32_e32 v127, v2
	v_mov_b32_e32 v128, v2
	v_mov_b32_e32 v129, v2
	.p2align	6

; #define AT_ISSUE_K(tt) do { const unsigned so_ = (unsigned)(((tt) & 3) * AT_SLOT); const bf16_t* kp_ = kgp + (size_t)(tt) * 64 * DM; \
;         glds16(kp_, (unsigned)__builtin_amdgcn_readfirstlane(kdst + so_)); glds16(kp_ + kx1, (unsigned)__builtin_amdgcn_readfirstlane(kdst + so_ + 1024)); } while (0)
; #define AT_ISSUE_V(tt) do { const unsigned so_ = (unsigned)(((tt) & 3) * AT_SLOT); const bf16_t* vp_ = vgp + (tt) * 64; \
;         glds16(vp_, (unsigned)__builtin_amdgcn_readfirstlane(vdst + so_)); glds16(vp_ + vx1, (unsigned)__builtin_amdgcn_readfirstlane(vdst + so_ + 1024)); } while (0)
; #define AT_BAR(N) asm volatile("s_waitcnt vmcnt(" #N ") lgkmcnt(0)\n\ts_barrier" ::: "memory")
; template <bool STORE> __device__ __forceinline__ void attn_unit(LAS unsigned char* lds, bf16_t* Q, const bf16_t* Kg, const bf16_t* VT, const float* subg, float lam, float outscale, int unit, const int wave_s) {
;     ...
;     AT_ISSUE_K(0); AT_ISSUE_V(0); AT_ISSUE_K(1); AT_ISSUE_V(1); AT_ISSUE_K(2); AT_ISSUE_V(2); AT_ISSUE_K(3);
;     AT_BAR(8);
;     f32x16 o[4]; o[0] = f32x16{}; o[1] = f32x16{}; o[2] = f32x16{}; o[3] = f32x16{};
;     float mref = sself + 6.0f, lsum = 0.f;
;     const int koff = q * 256 + (((map * 8 + hi) ^ (q & 15)) << 4), voff = AT_VOFF + q * 128 + ((hi ^ ((q >> 1) & 7)) << 4);
;     const float qposf = (float)(qrow0 + q - 4 * hi);
;     f32x16 x0, x1, n0, n1;
;     ...
;         int t = 0;
;         for (; t + 2 < td; t += 2) { AT_BODY(0, t, 1.0f, x0, x1, n0, n1); AT_BODY(0, t + 1, 1.0f, n0, n1, x0, x1); }
.LBB0_581:
	v_lshlrev_b32_e32 v0, 7, v3
	v_lshrrev_b32_e32 v3, 1, v219
	v_bitop3_b32 v2, v2, v3, 7 bitop3:0x78
	s_lshr_b32 s16, s12, 6
	v_lshl_or_b32 v215, v2, 4, v0
	s_waitcnt lgkmcnt(0)
	s_barrier
	s_cmpk_lt_u32 s12, 0xc0
	s_mov_b64 s[12:13], 0xf80
	v_or_b32_e32 v214, 0x10000, v215
	v_lshl_add_u64 v[174:175], v[182:183], 0, s[12:13]
	v_add_f32_e32 v167, v166, v166
	v_add_u32_e32 v204, 0, v214
	v_lshl_add_u64 v[176:177], v[172:173], 1, v[174:175]
	v_fma_f32 v185, 2.0, v166, v167
	v_xor_b32_e32 v203, 0x10020, v215
	v_xor_b32_e32 v202, 0x10040, v215
	v_xor_b32_e32 v179, 0x10060, v215
	s_cbranch_scc1 .LBB0_605
	v_xor_b32_e32 v0, 0x10020, v215
	v_readlane_b32 s12, v253, 23
	v_mov_b32_e32 v184, v166
	v_mov_b32_e32 v2, v167
	v_mov_b32_e32 v3, v185
	v_add_u32_e32 v220, 0, v0
	v_xor_b32_e32 v0, 0x10040, v215
	s_add_i32 s12, s34, s12
	v_add_f32_e32 v186, v184, v2
	v_add_f32_e32 v187, v185, v3
	v_add_u32_e32 v221, 0, v0
	v_xor_b32_e32 v0, 0x10060, v215
	v_add_u32_e32 v2, s12, v216
	v_add_u32_e32 v222, 0, v0
	v_ashrrev_i32_e32 v3, 31, v2
	v_add_u32_e32 v0, s19, v218
	v_lshlrev_b64 v[188:189], 11, v[2:3]
	v_lshlrev_b64 v[2:3], 15, v[0:1]
	v_lshl_or_b32 v2, v217, 4, v2
	v_mov_b32_e32 v14, v1
	v_mov_b32_e32 v15, v1
	v_add_f32_e32 v168, v187, v187
	s_and_b32 s12, s18, 0x700
	v_lshl_add_u64 v[190:191], s[34:35], 1, v[2:3]
	v_mov_b32_e32 v0, v1
	v_mov_b32_e32 v2, v1
	v_mov_b32_e32 v3, v1
	v_mov_b32_e32 v4, v1
	v_mov_b32_e32 v5, v1
	v_mov_b32_e32 v6, v1
	v_mov_b32_e32 v7, v1
	v_mov_b32_e32 v8, v1
	v_mov_b32_e32 v9, v1
	v_mov_b32_e32 v10, v1
	v_mov_b32_e32 v11, v1
	v_mov_b32_e32 v12, v1
	v_mov_b32_e32 v13, v1
	v_mov_b64_e32 v[78:79], v[14:15]
	v_mov_b64_e32 v[62:63], v[14:15]
	v_mov_b64_e32 v[46:47], v[14:15]
	v_mov_b64_e32 v[30:31], v[14:15]
	v_fmac_f32_e32 v168, 2.0, v187
	v_or3_b32 v188, v188, s12, v178
	s_mov_b32 s20, 0
	v_mov_b32_e32 v184, 0
	s_mov_b32 s21, 0x14000
	s_movk_i32 s28, 0x80
	v_mov_b64_e32 v[76:77], v[12:13]
	v_mov_b64_e32 v[74:75], v[10:11]
	v_mov_b64_e32 v[72:73], v[8:9]
	v_mov_b64_e32 v[70:71], v[6:7]
	v_mov_b64_e32 v[68:69], v[4:5]
	v_mov_b64_e32 v[66:67], v[2:3]
	v_mov_b64_e32 v[64:65], v[0:1]
	v_mov_b64_e32 v[60:61], v[12:13]
	v_mov_b64_e32 v[58:59], v[10:11]
	v_mov_b64_e32 v[56:57], v[8:9]
	v_mov_b64_e32 v[54:55], v[6:7]
	v_mov_b64_e32 v[52:53], v[4:5]
	v_mov_b64_e32 v[50:51], v[2:3]
	v_mov_b64_e32 v[48:49], v[0:1]
	v_mov_b64_e32 v[44:45], v[12:13]
	v_mov_b64_e32 v[42:43], v[10:11]
	v_mov_b64_e32 v[40:41], v[8:9]
	v_mov_b64_e32 v[38:39], v[6:7]
	v_mov_b64_e32 v[36:37], v[4:5]
	v_mov_b64_e32 v[34:35], v[2:3]
	v_mov_b64_e32 v[32:33], v[0:1]
	v_mov_b64_e32 v[28:29], v[12:13]
	v_mov_b64_e32 v[26:27], v[10:11]
	v_mov_b64_e32 v[24:25], v[8:9]
	v_mov_b64_e32 v[22:23], v[6:7]
	v_mov_b64_e32 v[20:21], v[4:5]
	v_mov_b64_e32 v[18:19], v[2:3]
	v_mov_b64_e32 v[16:17], v[0:1]
	.p2align	6

; template <bool STORE> __device__ __forceinline__ void attn_unit(LAS unsigned char* lds, bf16_t* Q, const bf16_t* Kg, const bf16_t* VT, const float* subg, float lam, float outscale, int unit, const int wave_s) {
;     ...
;         int t = 0;
;         for (; t + 2 < td; t += 2) { AT_BODY(0, t, 1.0f, x0, x1, n0, n1); AT_BODY(0, t + 1, 1.0f, n0, n1, x0, x1); }
.LBB0_634:
	s_add_i32 s16, s16, 2
	s_add_i32 s20, s20, 0x8000
	v_lshl_add_u64 v[4:5], v[4:5], 0, s[26:27]
	v_lshl_add_u64 v[6:7], v[6:7], 0, s[24:25]
	s_andn2_b64 vcc, exec, s[12:13]
	s_addk_i32 s18, 0x80
	s_cbranch_vccz .LBB0_659
	.p2align	6
